# k16 + MLA down-projection (T1) epilogue rewritten: row rstd from an LDS table, packed square sums, one permlane32/16-swap reduction + 2 stores for the per-row sum-of-squares outputs
# speedup vs baseline: 1.0055x; 1.0055x over previous
; __device__ __forceinline__ unsigned cvtpk(float lo, float hi) { f32x2_t v = {lo, hi}; bf16x2_t b = __builtin_convertvector(v, bf16x2_t); return __builtin_bit_cast(unsigned, b); }
;     __device__ __forceinline__ void operator()(const f32x4 (&acc)[2][2][4][2], const Unit& u, int wr, int wc, int fr, int fq) const {
;         const int row0 = u.pm * BM + wr * 64 + fr, col0 = u.pn * BM + wc * 32 + 8 * fq;
;         float* so = (u.pn == 0) ? ssq_o[0] : (u.pn == 1) ? ssq_o[1] : (u.pn == 2) ? ssq_o[2] : (u.pn == 3) ? ssq_o[3] : nullptr;
; #pragma unroll
;         for (int ai = 0; ai < 2; ++ai)
; #pragma unroll
;             for (int m = 0; m < 4; ++m) {
;                 const int row = row0 + ai * HALF + m * 16; float s = 0.f;
;                 const float rs = ssq_in ? 1.0f / sqrtf(ssq_sum(ssq_in + (size_t)row * 16) * inv_dim + EPS) : 1.0f;
; #pragma unroll
;                 for (int bj = 0; bj < 2; ++bj) {
;                     int col = col0 + bj * HALF; if (hd_in) col = (col / hd_in) * hd_out + (col % hd_in);
;                     const f32x4 v0 = acc[ai][bj][m][0] * rs, v1 = acc[ai][bj][m][1] * rs;
;                     u32x4 w; w.x = cvtpk(v0[0], v0[1]); w.y = cvtpk(v0[2], v0[3]); w.z = cvtpk(v1[0], v1[1]); w.w = cvtpk(v1[2], v1[3]);
;                     *(u32x4*)(O + (size_t)row * ldc + col) = w;
;                     s += (v0[0] * v0[0] + v0[1] * v0[1]) + (v0[2] * v0[2] + v0[3] * v0[3]) + (v1[0] * v1[0] + v1[1] * v1[1]) + (v1[2] * v1[2] + v1[3] * v1[3]);
;                 }
.LBB0_1422:
	v_readlane_b32 vcc_lo, v254, 7
	v_mbcnt_lo_u32_b32 v160, -1, 0
	v_mbcnt_hi_u32_b32 v160, -1, v160
	v_lshrrev_b32_e32 v161, 1, v160
	v_lshl_add_u32 v161, vcc_lo, 5, v161
	v_and_b32_e32 v162, 1, v160
	v_lshl_add_u32 v163, s12, 8, v161
	v_lshlrev_b32_e32 v163, 6, v163
	v_lshl_add_u32 v163, v162, 5, v163
	global_load_dwordx4 v[164:167], v163, s[20:21]
	global_load_dwordx4 v[168:171], v163, s[20:21] offset:16
	v_lshl_add_u32 v172, s12, 8, v150
	v_lshlrev_b32_e32 v172, 11, v172
	v_lshl_or_b32 v173, s10, 8, v152
	v_lshl_add_u32 v172, v173, 1, v172
	s_lshl_b32 s10, s10, 4
	s_and_b32 s10, s10, 16
	s_add_u32 s10, s44, s10
	s_addc_u32 s11, s45, 0
	s_add_u32 s40, s10, s56
	s_addc_u32 s41, s11, 0
	v_lshlrev_b32_e32 v161, 2, v161
	v_add_u32_e32 v161, 0x20100, v161
	v_lshlrev_b32_e32 v162, 2, v150
	v_add_u32_e32 v162, 0x20100, v162
	s_waitcnt vmcnt(0)
	v_pk_add_f32 v[164:165], v[164:165], v[166:167]
	v_pk_add_f32 v[168:169], v[168:169], v[170:171]
	v_pk_add_f32 v[164:165], v[164:165], v[168:169]
	v_add_f32_e32 v164, v164, v165
	s_nop 1
	v_add_f32_dpp v164, v164, v164 quad_perm:[1,0,3,2] row_mask:0xf bank_mask:0xf
	v_fmamk_f32 v164, v164, 0x3a800000, v156
	v_rsq_f32_e32 v164, v164
	s_nop 0
	ds_write_b32 v161, v164
	s_waitcnt lgkmcnt(0)
	s_barrier
	ds_read_b32 v174, v162 offset:0
	ds_read_b32 v175, v162 offset:64
	ds_read_b32 v176, v162 offset:128
	ds_read_b32 v177, v162 offset:192
	ds_read_b32 v178, v162 offset:512
	ds_read_b32 v179, v162 offset:576
	ds_read_b32 v144, v162 offset:640
	ds_read_b32 v145, v162 offset:704
	s_waitcnt lgkmcnt(7)
	v_mul_f32_e32 v124, v174, v124
	v_mul_f32_e32 v125, v174, v125
	v_mul_f32_e32 v126, v174, v126
	v_mul_f32_e32 v127, v174, v127
	v_mul_f32_e32 v120, v174, v120
	v_mul_f32_e32 v121, v174, v121
	v_mul_f32_e32 v122, v174, v122
	v_mul_f32_e32 v123, v174, v123
	v_mul_f32_e32 v116, v174, v116
	v_mul_f32_e32 v117, v174, v117
	v_mul_f32_e32 v118, v174, v118
	v_mul_f32_e32 v119, v174, v119
	v_mul_f32_e32 v112, v174, v112
	v_mul_f32_e32 v113, v174, v113
	v_mul_f32_e32 v114, v174, v114
	v_mul_f32_e32 v115, v174, v115
	v_pk_mul_f32 v[168:169], v[124:125], v[124:125]
	v_pk_fma_f32 v[168:169], v[126:127], v[126:127], v[168:169]
	v_pk_fma_f32 v[168:169], v[120:121], v[120:121], v[168:169]
	v_pk_fma_f32 v[168:169], v[122:123], v[122:123], v[168:169]
	v_pk_mul_f32 v[170:171], v[116:117], v[116:117]
	v_pk_fma_f32 v[170:171], v[118:119], v[118:119], v[170:171]
	v_pk_fma_f32 v[170:171], v[112:113], v[112:113], v[170:171]
	v_pk_fma_f32 v[170:171], v[114:115], v[114:115], v[170:171]
	v_cvt_pk_bf16_f32 v124, v124, v125
	v_cvt_pk_bf16_f32 v125, v126, v127
	v_cvt_pk_bf16_f32 v126, v120, v121
	v_cvt_pk_bf16_f32 v127, v122, v123
	v_cvt_pk_bf16_f32 v116, v116, v117
	v_cvt_pk_bf16_f32 v117, v118, v119
	v_cvt_pk_bf16_f32 v118, v112, v113
	v_cvt_pk_bf16_f32 v119, v114, v115
	global_store_dwordx4 v172, v[124:127], s[18:19]
	global_store_dwordx4 v172, v[116:119], s[18:19] offset:256
	v_pk_add_f32 v[168:169], v[168:169], v[170:171]
	v_add_f32_e32 v160, v168, v169
	s_waitcnt lgkmcnt(6)
	v_mul_f32_e32 v108, v175, v108
	v_mul_f32_e32 v109, v175, v109
	v_mul_f32_e32 v110, v175, v110
	v_mul_f32_e32 v111, v175, v111
	v_mul_f32_e32 v104, v175, v104
	v_mul_f32_e32 v105, v175, v105
	v_mul_f32_e32 v106, v175, v106
	v_mul_f32_e32 v107, v175, v107
	v_mul_f32_e32 v100, v175, v100
	v_mul_f32_e32 v101, v175, v101
	v_mul_f32_e32 v102, v175, v102
	v_mul_f32_e32 v103, v175, v103
	v_mul_f32_e32 v96, v175, v96
	v_mul_f32_e32 v97, v175, v97
	v_mul_f32_e32 v98, v175, v98
	v_mul_f32_e32 v99, v175, v99
	v_pk_mul_f32 v[168:169], v[108:109], v[108:109]
	v_pk_fma_f32 v[168:169], v[110:111], v[110:111], v[168:169]
	v_pk_fma_f32 v[168:169], v[104:105], v[104:105], v[168:169]
	v_pk_fma_f32 v[168:169], v[106:107], v[106:107], v[168:169]
	v_pk_mul_f32 v[170:171], v[100:101], v[100:101]
	v_pk_fma_f32 v[170:171], v[102:103], v[102:103], v[170:171]
	v_pk_fma_f32 v[170:171], v[96:97], v[96:97], v[170:171]
	v_pk_fma_f32 v[170:171], v[98:99], v[98:99], v[170:171]
	v_cvt_pk_bf16_f32 v108, v108, v109
	v_cvt_pk_bf16_f32 v109, v110, v111
	v_cvt_pk_bf16_f32 v110, v104, v105
	v_cvt_pk_bf16_f32 v111, v106, v107
	v_cvt_pk_bf16_f32 v100, v100, v101
	v_cvt_pk_bf16_f32 v101, v102, v103
	v_cvt_pk_bf16_f32 v102, v96, v97
	v_cvt_pk_bf16_f32 v103, v98, v99
	v_add_u32_e32 v173, 0x8000, v172
	global_store_dwordx4 v173, v[108:111], s[18:19]
	global_store_dwordx4 v173, v[100:103], s[18:19] offset:256
	v_pk_add_f32 v[168:169], v[168:169], v[170:171]
	v_add_f32_e32 v161, v168, v169
	s_waitcnt lgkmcnt(5)
	v_mul_f32_e32 v92, v176, v92
	v_mul_f32_e32 v93, v176, v93
	v_mul_f32_e32 v94, v176, v94
	v_mul_f32_e32 v95, v176, v95
	v_mul_f32_e32 v88, v176, v88
	v_mul_f32_e32 v89, v176, v89
	v_mul_f32_e32 v90, v176, v90
	v_mul_f32_e32 v91, v176, v91
	v_mul_f32_e32 v84, v176, v84
	v_mul_f32_e32 v85, v176, v85
	v_mul_f32_e32 v86, v176, v86
	v_mul_f32_e32 v87, v176, v87
	v_mul_f32_e32 v80, v176, v80
	v_mul_f32_e32 v81, v176, v81
	v_mul_f32_e32 v82, v176, v82
	v_mul_f32_e32 v83, v176, v83
	v_pk_mul_f32 v[168:169], v[92:93], v[92:93]
	v_pk_fma_f32 v[168:169], v[94:95], v[94:95], v[168:169]
	v_pk_fma_f32 v[168:169], v[88:89], v[88:89], v[168:169]
	v_pk_fma_f32 v[168:169], v[90:91], v[90:91], v[168:169]
	v_pk_mul_f32 v[170:171], v[84:85], v[84:85]
	v_pk_fma_f32 v[170:171], v[86:87], v[86:87], v[170:171]
	v_pk_fma_f32 v[170:171], v[80:81], v[80:81], v[170:171]
	v_pk_fma_f32 v[170:171], v[82:83], v[82:83], v[170:171]
	v_cvt_pk_bf16_f32 v92, v92, v93
	v_cvt_pk_bf16_f32 v93, v94, v95
	v_cvt_pk_bf16_f32 v94, v88, v89
	v_cvt_pk_bf16_f32 v95, v90, v91
	v_cvt_pk_bf16_f32 v84, v84, v85
	v_cvt_pk_bf16_f32 v85, v86, v87
	v_cvt_pk_bf16_f32 v86, v80, v81
	v_cvt_pk_bf16_f32 v87, v82, v83
	v_add_u32_e32 v173, 0x10000, v172
	global_store_dwordx4 v173, v[92:95], s[18:19]
	global_store_dwordx4 v173, v[84:87], s[18:19] offset:256
	v_pk_add_f32 v[168:169], v[168:169], v[170:171]
	v_add_f32_e32 v162, v168, v169
	s_waitcnt lgkmcnt(4)
; __device__ __forceinline__ unsigned cvtpk(float lo, float hi) { f32x2_t v = {lo, hi}; bf16x2_t b = __builtin_convertvector(v, bf16x2_t); return __builtin_bit_cast(unsigned, b); }
;     __device__ __forceinline__ void operator()(const f32x4 (&acc)[2][2][4][2], const Unit& u, int wr, int wc, int fr, int fq) const {
;     ...
;                 const int row = row0 + ai * HALF + m * 16; float s = 0.f;
;                 const float rs = ssq_in ? 1.0f / sqrtf(ssq_sum(ssq_in + (size_t)row * 16) * inv_dim + EPS) : 1.0f;
; #pragma unroll
;                 for (int bj = 0; bj < 2; ++bj) {
;                     int col = col0 + bj * HALF; if (hd_in) col = (col / hd_in) * hd_out + (col % hd_in);
;                     const f32x4 v0 = acc[ai][bj][m][0] * rs, v1 = acc[ai][bj][m][1] * rs;
;                     u32x4 w; w.x = cvtpk(v0[0], v0[1]); w.y = cvtpk(v0[2], v0[3]); w.z = cvtpk(v1[0], v1[1]); w.w = cvtpk(v1[2], v1[3]);
;                     *(u32x4*)(O + (size_t)row * ldc + col) = w;
;                     s += (v0[0] * v0[0] + v0[1] * v0[1]) + (v0[2] * v0[2] + v0[3] * v0[3]) + (v1[0] * v1[0] + v1[1] * v1[1]) + (v1[2] * v1[2] + v1[3] * v1[3]);
;                 }
	v_mul_f32_e32 v76, v177, v76
	v_mul_f32_e32 v77, v177, v77
	v_mul_f32_e32 v78, v177, v78
	v_mul_f32_e32 v79, v177, v79
	v_mul_f32_e32 v72, v177, v72
	v_mul_f32_e32 v73, v177, v73
	v_mul_f32_e32 v74, v177, v74
	v_mul_f32_e32 v75, v177, v75
	v_mul_f32_e32 v68, v177, v68
	v_mul_f32_e32 v69, v177, v69
	v_mul_f32_e32 v70, v177, v70
	v_mul_f32_e32 v71, v177, v71
	v_mul_f32_e32 v64, v177, v64
	v_mul_f32_e32 v65, v177, v65
	v_mul_f32_e32 v66, v177, v66
	v_mul_f32_e32 v67, v177, v67
	v_pk_mul_f32 v[168:169], v[76:77], v[76:77]
	v_pk_fma_f32 v[168:169], v[78:79], v[78:79], v[168:169]
	v_pk_fma_f32 v[168:169], v[72:73], v[72:73], v[168:169]
	v_pk_fma_f32 v[168:169], v[74:75], v[74:75], v[168:169]
	v_pk_mul_f32 v[170:171], v[68:69], v[68:69]
	v_pk_fma_f32 v[170:171], v[70:71], v[70:71], v[170:171]
	v_pk_fma_f32 v[170:171], v[64:65], v[64:65], v[170:171]
	v_pk_fma_f32 v[170:171], v[66:67], v[66:67], v[170:171]
	v_cvt_pk_bf16_f32 v76, v76, v77
	v_cvt_pk_bf16_f32 v77, v78, v79
	v_cvt_pk_bf16_f32 v78, v72, v73
	v_cvt_pk_bf16_f32 v79, v74, v75
	v_cvt_pk_bf16_f32 v68, v68, v69
	v_cvt_pk_bf16_f32 v69, v70, v71
	v_cvt_pk_bf16_f32 v70, v64, v65
	v_cvt_pk_bf16_f32 v71, v66, v67
	v_add_u32_e32 v173, 0x18000, v172
	global_store_dwordx4 v173, v[76:79], s[18:19]
	global_store_dwordx4 v173, v[68:71], s[18:19] offset:256
	v_pk_add_f32 v[168:169], v[168:169], v[170:171]
	v_add_f32_e32 v163, v168, v169
	s_waitcnt lgkmcnt(3)
	v_mul_f32_e32 v60, v178, v60
	v_mul_f32_e32 v61, v178, v61
	v_mul_f32_e32 v62, v178, v62
	v_mul_f32_e32 v63, v178, v63
	v_mul_f32_e32 v56, v178, v56
	v_mul_f32_e32 v57, v178, v57
	v_mul_f32_e32 v58, v178, v58
	v_mul_f32_e32 v59, v178, v59
	v_mul_f32_e32 v52, v178, v52
	v_mul_f32_e32 v53, v178, v53
	v_mul_f32_e32 v54, v178, v54
	v_mul_f32_e32 v55, v178, v55
	v_mul_f32_e32 v48, v178, v48
	v_mul_f32_e32 v49, v178, v49
	v_mul_f32_e32 v50, v178, v50
	v_mul_f32_e32 v51, v178, v51
	v_pk_mul_f32 v[168:169], v[60:61], v[60:61]
	v_pk_fma_f32 v[168:169], v[62:63], v[62:63], v[168:169]
	v_pk_fma_f32 v[168:169], v[56:57], v[56:57], v[168:169]
	v_pk_fma_f32 v[168:169], v[58:59], v[58:59], v[168:169]
	v_pk_mul_f32 v[170:171], v[52:53], v[52:53]
	v_pk_fma_f32 v[170:171], v[54:55], v[54:55], v[170:171]
	v_pk_fma_f32 v[170:171], v[48:49], v[48:49], v[170:171]
	v_pk_fma_f32 v[170:171], v[50:51], v[50:51], v[170:171]
	v_cvt_pk_bf16_f32 v60, v60, v61
	v_cvt_pk_bf16_f32 v61, v62, v63
	v_cvt_pk_bf16_f32 v62, v56, v57
	v_cvt_pk_bf16_f32 v63, v58, v59
	v_cvt_pk_bf16_f32 v52, v52, v53
	v_cvt_pk_bf16_f32 v53, v54, v55
	v_cvt_pk_bf16_f32 v54, v48, v49
	v_cvt_pk_bf16_f32 v55, v50, v51
	v_add_u32_e32 v173, 0x40000, v172
	global_store_dwordx4 v173, v[60:63], s[18:19]
	global_store_dwordx4 v173, v[52:55], s[18:19] offset:256
	v_pk_add_f32 v[168:169], v[168:169], v[170:171]
	v_add_f32_e32 v164, v168, v169
	s_waitcnt lgkmcnt(2)
	v_mul_f32_e32 v44, v179, v44
	v_mul_f32_e32 v45, v179, v45
	v_mul_f32_e32 v46, v179, v46
	v_mul_f32_e32 v47, v179, v47
	v_mul_f32_e32 v40, v179, v40
	v_mul_f32_e32 v41, v179, v41
	v_mul_f32_e32 v42, v179, v42
	v_mul_f32_e32 v43, v179, v43
	v_mul_f32_e32 v36, v179, v36
	v_mul_f32_e32 v37, v179, v37
	v_mul_f32_e32 v38, v179, v38
	v_mul_f32_e32 v39, v179, v39
	v_mul_f32_e32 v32, v179, v32
	v_mul_f32_e32 v33, v179, v33
	v_mul_f32_e32 v34, v179, v34
	v_mul_f32_e32 v35, v179, v35
	v_pk_mul_f32 v[168:169], v[44:45], v[44:45]
	v_pk_fma_f32 v[168:169], v[46:47], v[46:47], v[168:169]
	v_pk_fma_f32 v[168:169], v[40:41], v[40:41], v[168:169]
	v_pk_fma_f32 v[168:169], v[42:43], v[42:43], v[168:169]
	v_pk_mul_f32 v[170:171], v[36:37], v[36:37]
	v_pk_fma_f32 v[170:171], v[38:39], v[38:39], v[170:171]
	v_pk_fma_f32 v[170:171], v[32:33], v[32:33], v[170:171]
	v_pk_fma_f32 v[170:171], v[34:35], v[34:35], v[170:171]
	v_cvt_pk_bf16_f32 v44, v44, v45
	v_cvt_pk_bf16_f32 v45, v46, v47
	v_cvt_pk_bf16_f32 v46, v40, v41
	v_cvt_pk_bf16_f32 v47, v42, v43
	v_cvt_pk_bf16_f32 v36, v36, v37
	v_cvt_pk_bf16_f32 v37, v38, v39
	v_cvt_pk_bf16_f32 v38, v32, v33
	v_cvt_pk_bf16_f32 v39, v34, v35
	v_add_u32_e32 v173, 0x48000, v172
	global_store_dwordx4 v173, v[44:47], s[18:19]
	global_store_dwordx4 v173, v[36:39], s[18:19] offset:256
	v_pk_add_f32 v[168:169], v[168:169], v[170:171]
	v_add_f32_e32 v165, v168, v169
	s_waitcnt lgkmcnt(1)
; __device__ __forceinline__ unsigned cvtpk(float lo, float hi) { f32x2_t v = {lo, hi}; bf16x2_t b = __builtin_convertvector(v, bf16x2_t); return __builtin_bit_cast(unsigned, b); }
;     __device__ __forceinline__ void operator()(const f32x4 (&acc)[2][2][4][2], const Unit& u, int wr, int wc, int fr, int fq) const {
;     ...
;                 for (int bj = 0; bj < 2; ++bj) {
;                     int col = col0 + bj * HALF; if (hd_in) col = (col / hd_in) * hd_out + (col % hd_in);
;                     const f32x4 v0 = acc[ai][bj][m][0] * rs, v1 = acc[ai][bj][m][1] * rs;
;                     u32x4 w; w.x = cvtpk(v0[0], v0[1]); w.y = cvtpk(v0[2], v0[3]); w.z = cvtpk(v1[0], v1[1]); w.w = cvtpk(v1[2], v1[3]);
;                     *(u32x4*)(O + (size_t)row * ldc + col) = w;
;                     s += (v0[0] * v0[0] + v0[1] * v0[1]) + (v0[2] * v0[2] + v0[3] * v0[3]) + (v1[0] * v1[0] + v1[1] * v1[1]) + (v1[2] * v1[2] + v1[3] * v1[3]);
;                 }
;                 if (so) { s += __shfl_xor(s, 16); s += __shfl_xor(s, 32); if (fq == 0) so[(size_t)row * 16 + (u.pn & 1) * 4 + wc] = s; }
	v_mul_f32_e32 v28, v144, v28
	v_mul_f32_e32 v29, v144, v29
	v_mul_f32_e32 v30, v144, v30
	v_mul_f32_e32 v31, v144, v31
	v_mul_f32_e32 v24, v144, v24
	v_mul_f32_e32 v25, v144, v25
	v_mul_f32_e32 v26, v144, v26
	v_mul_f32_e32 v27, v144, v27
	v_mul_f32_e32 v20, v144, v20
	v_mul_f32_e32 v21, v144, v21
	v_mul_f32_e32 v22, v144, v22
	v_mul_f32_e32 v23, v144, v23
	v_mul_f32_e32 v16, v144, v16
	v_mul_f32_e32 v17, v144, v17
	v_mul_f32_e32 v18, v144, v18
	v_mul_f32_e32 v19, v144, v19
	v_pk_mul_f32 v[168:169], v[28:29], v[28:29]
	v_pk_fma_f32 v[168:169], v[30:31], v[30:31], v[168:169]
	v_pk_fma_f32 v[168:169], v[24:25], v[24:25], v[168:169]
	v_pk_fma_f32 v[168:169], v[26:27], v[26:27], v[168:169]
	v_pk_mul_f32 v[170:171], v[20:21], v[20:21]
	v_pk_fma_f32 v[170:171], v[22:23], v[22:23], v[170:171]
	v_pk_fma_f32 v[170:171], v[16:17], v[16:17], v[170:171]
	v_pk_fma_f32 v[170:171], v[18:19], v[18:19], v[170:171]
	v_cvt_pk_bf16_f32 v28, v28, v29
	v_cvt_pk_bf16_f32 v29, v30, v31
	v_cvt_pk_bf16_f32 v30, v24, v25
	v_cvt_pk_bf16_f32 v31, v26, v27
	v_cvt_pk_bf16_f32 v20, v20, v21
	v_cvt_pk_bf16_f32 v21, v22, v23
	v_cvt_pk_bf16_f32 v22, v16, v17
	v_cvt_pk_bf16_f32 v23, v18, v19
	v_add_u32_e32 v173, 0x50000, v172
	global_store_dwordx4 v173, v[28:31], s[18:19]
	global_store_dwordx4 v173, v[20:23], s[18:19] offset:256
	v_pk_add_f32 v[168:169], v[168:169], v[170:171]
	v_add_f32_e32 v166, v168, v169
	s_waitcnt lgkmcnt(0)
	v_mul_f32_e32 v12, v145, v12
	v_mul_f32_e32 v13, v145, v13
	v_mul_f32_e32 v14, v145, v14
	v_mul_f32_e32 v15, v145, v15
	v_mul_f32_e32 v8, v145, v8
	v_mul_f32_e32 v9, v145, v9
	v_mul_f32_e32 v10, v145, v10
	v_mul_f32_e32 v11, v145, v11
	v_mul_f32_e32 v4, v145, v4
	v_mul_f32_e32 v5, v145, v5
	v_mul_f32_e32 v6, v145, v6
	v_mul_f32_e32 v7, v145, v7
	v_mul_f32_e32 v0, v145, v0
	v_mul_f32_e32 v1, v145, v1
	v_mul_f32_e32 v2, v145, v2
	v_mul_f32_e32 v3, v145, v3
	v_pk_mul_f32 v[168:169], v[12:13], v[12:13]
	v_pk_fma_f32 v[168:169], v[14:15], v[14:15], v[168:169]
	v_pk_fma_f32 v[168:169], v[8:9], v[8:9], v[168:169]
	v_pk_fma_f32 v[168:169], v[10:11], v[10:11], v[168:169]
	v_pk_mul_f32 v[170:171], v[4:5], v[4:5]
	v_pk_fma_f32 v[170:171], v[6:7], v[6:7], v[170:171]
	v_pk_fma_f32 v[170:171], v[0:1], v[0:1], v[170:171]
	v_pk_fma_f32 v[170:171], v[2:3], v[2:3], v[170:171]
	v_cvt_pk_bf16_f32 v12, v12, v13
	v_cvt_pk_bf16_f32 v13, v14, v15
	v_cvt_pk_bf16_f32 v14, v8, v9
	v_cvt_pk_bf16_f32 v15, v10, v11
	v_cvt_pk_bf16_f32 v4, v4, v5
	v_cvt_pk_bf16_f32 v5, v6, v7
	v_cvt_pk_bf16_f32 v6, v0, v1
	v_cvt_pk_bf16_f32 v7, v2, v3
	v_add_u32_e32 v173, 0x58000, v172
	global_store_dwordx4 v173, v[12:15], s[18:19]
	global_store_dwordx4 v173, v[4:7], s[18:19] offset:256
	v_pk_add_f32 v[168:169], v[168:169], v[170:171]
	v_add_f32_e32 v167, v168, v169
	s_cmp_eq_u64 s[44:45], 0
	s_cbranch_scc1 .Lk16_t1_noss
	v_mbcnt_lo_u32_b32 v146, -1, 0
	v_mbcnt_hi_u32_b32 v146, -1, v146
	v_lshl_add_u32 v159, s12, 8, v150
	v_lshrrev_b32_e32 v147, 4, v146
	v_and_b32_e32 v148, 1, v147
	v_lshlrev_b32_e32 v148, 5, v148
	v_lshrrev_b32_e32 v147, 1, v147
	v_lshl_add_u32 v148, v147, 4, v148
	v_add_u32_e32 v148, v159, v148
	v_lshlrev_b32_e32 v148, 6, v148
	v_add_u32_e32 v149, 0x2000, v148
	v_permlane32_swap_b32_e32 v160, v161
	v_permlane32_swap_b32_e32 v162, v163
	v_permlane32_swap_b32_e32 v164, v165
	v_permlane32_swap_b32_e32 v166, v167
	v_add_f32_e32 v160, v160, v161
	v_add_f32_e32 v162, v162, v163
	v_add_f32_e32 v164, v164, v165
	v_add_f32_e32 v166, v166, v167
	s_nop 1
	v_permlane16_swap_b32_e32 v160, v162
	v_permlane16_swap_b32_e32 v164, v166
	v_add_f32_e32 v160, v160, v162
	v_add_f32_e32 v164, v164, v166
	global_store_dword v148, v160, s[40:41]
	global_store_dword v149, v164, s[40:41]
.Lk16_t1_noss:
.LBB0_1454:
	s_andn2_b64 vcc, exec, s[8:9]
	s_mov_b64 s[8:9], -1
	s_cbranch_vccnz .LBB0_1405
	s_andn2_b64 vcc, exec, s[16:17]
	s_cbranch_vccnz .LBB0_1404
	s_barrier
	s_branch .LBB0_1404
